# lru_pass3 scans and carry prefixes rewritten with hoisted loads; mLSTM output MFMA chain LDS reads in flight
# speedup vs baseline: 1.0062x; 1.0062x over previous
; DI void lru_pass3(const Ctx& C, const bf16* LA, const bf16* BV, const f32x2* AGG, const bf16* PROJ, float* HT, bf16* YMIX) {
;     ...
;     for (int idx = gt; idx < BATCH * LNSEG * 512; idx += ngt) {
;         const int ch = (idx & 511) * 2, seg = (idx >> 9) & (LNSEG - 1), b = idx >> 15;
;         float h0 = 0.f, h1 = 0.f;
; #pragma unroll 8
;         for (int s = 0; s < seg; ++s) { const f32x4 e = *(const f32x4*)(AGG + ((size_t)((b * 2 + 0) * LNSEG + s)) * 1024 + ch); h0 = e.x * h0 + e.y; h1 = e.z * h1 + e.w; }
.LBB0_1342:
	v_mov_b32_e32 v46, 0x1000
	v_mov_b32_e32 v47, 0
	v_mov_b32_e32 v48, 0x2000
	v_mov_b32_e32 v49, 0
	v_bfe_u32 v29, v1, 9, 6
	v_lshlrev_b32_e32 v2, 1, v1
	v_lshrrev_b32_e32 v13, 9, v1
	v_and_b32_e32 v12, 0x3fe, v2
	v_ashrrev_i32_e32 v10, 15, v1
	v_cmp_ne_u32_e32 vcc, 0, v29
	s_and_saveexec_b64 s[8:9], vcc
	s_xor_b64 s[8:9], exec, s[8:9]
	s_cbranch_execz .LBB0_1352
	v_lshlrev_b32_e32 v2, 3, v28
	v_and_b32_e32 v11, 0x1ff0, v2
	v_add_u32_e32 v2, -1, v29
	v_cmp_lt_u32_e32 vcc, 6, v2
	v_mov_b32_e32 v2, v3
	v_lshlrev_b32_e32 v6, 7, v10
	v_mov_b32_e32 v16, 0
	v_mov_b64_e32 v[24:25], v[2:3]
	s_and_saveexec_b64 s[10:11], vcc
	s_cbranch_execz .LBB0_1347
	v_ashrrev_i32_e32 v7, 31, v6
	v_lshlrev_b64 v[14:15], 13, v[6:7]
	v_lshlrev_b32_e32 v2, 3, v12
	v_or_b32_e32 v14, v14, v11
	v_mov_b32_e32 v24, 0
	v_lshl_add_u64 v[8:9], s[40:41], 0, v[2:3]
	v_and_b32_e32 v16, 56, v13
	v_lshl_add_u64 v[14:15], s[44:45], 0, v[14:15]
	s_mov_b32 s14, 0
	s_mov_b64 s[12:13], 0
	v_mov_b32_e32 v25, v24
	s_mov_b64 s[16:17], 0x10000
.LBB0_1345:
	v_add_co_u32_e32 v18, vcc, 0xffffc000, v14
	s_nop 1
	v_addc_co_u32_e32 v19, vcc, -1, v15, vcc
	global_load_dwordx4 v[164:167], v[18:19], off
	v_lshl_add_u64 v[18:19], v[18:19], 0, v[48:49]
	global_load_dwordx4 v[168:171], v[18:19], off
	v_lshl_add_u64 v[18:19], v[18:19], 0, v[48:49]
	global_load_dwordx4 v[172:175], v[18:19], off
	v_lshl_add_u64 v[18:19], v[18:19], 0, v[48:49]
	global_load_dwordx4 v[176:179], v[18:19], off
	v_lshl_add_u64 v[18:19], v[18:19], 0, v[48:49]
	global_load_dwordx4 v[180:183], v[18:19], off
	v_lshl_add_u64 v[18:19], v[18:19], 0, v[48:49]
	global_load_dwordx4 v[184:187], v[18:19], off
	v_lshl_add_u64 v[18:19], v[18:19], 0, v[48:49]
	global_load_dwordx4 v[188:191], v[18:19], off
	v_lshl_add_u64 v[18:19], v[18:19], 0, v[48:49]
	global_load_dwordx4 v[192:195], v[18:19], off
	v_lshl_add_u64 v[18:19], v[18:19], 0, v[48:49]
	s_add_i32 s14, s14, 8
	v_cmp_eq_u32_e32 vcc, s14, v16
	s_or_b64 s[12:13], vcc, s[12:13]
	v_lshl_add_u64 v[14:15], v[14:15], 0, s[16:17]
	s_waitcnt vmcnt(7) lgkmcnt(0)
	v_mov_b32_e32 v22, v164
	v_mov_b32_e32 v23, v166
	v_mov_b32_e32 v20, v165
	v_mov_b32_e32 v21, v167
	v_pk_fma_f32 v[24:25], v[24:25], v[22:23], v[20:21]
	s_waitcnt vmcnt(6)
	v_mov_b32_e32 v22, v168
	v_mov_b32_e32 v23, v170
	v_mov_b32_e32 v20, v169
	v_mov_b32_e32 v21, v171
	v_pk_fma_f32 v[24:25], v[24:25], v[22:23], v[20:21]
	s_waitcnt vmcnt(5)
	v_mov_b32_e32 v22, v172
	v_mov_b32_e32 v23, v174
	v_mov_b32_e32 v20, v173
	v_mov_b32_e32 v21, v175
	v_pk_fma_f32 v[24:25], v[24:25], v[22:23], v[20:21]
	s_waitcnt vmcnt(4)
	v_mov_b32_e32 v22, v176
	v_mov_b32_e32 v23, v178
	v_mov_b32_e32 v20, v177
	v_mov_b32_e32 v21, v179
	v_pk_fma_f32 v[24:25], v[24:25], v[22:23], v[20:21]
	s_waitcnt vmcnt(3)
	v_mov_b32_e32 v22, v180
	v_mov_b32_e32 v23, v182
	v_mov_b32_e32 v20, v181
	v_mov_b32_e32 v21, v183
	v_pk_fma_f32 v[24:25], v[24:25], v[22:23], v[20:21]
	s_waitcnt vmcnt(2)
	v_mov_b32_e32 v22, v184
	v_mov_b32_e32 v23, v186
	v_mov_b32_e32 v20, v185
	v_mov_b32_e32 v21, v187
	v_pk_fma_f32 v[24:25], v[24:25], v[22:23], v[20:21]
	s_waitcnt vmcnt(1)
	v_mov_b32_e32 v22, v188
	v_mov_b32_e32 v23, v190
	v_mov_b32_e32 v20, v189
	v_mov_b32_e32 v21, v191
	v_pk_fma_f32 v[24:25], v[24:25], v[22:23], v[20:21]
	s_waitcnt vmcnt(0)
	v_mov_b32_e32 v22, v192
	v_mov_b32_e32 v23, v194
	v_mov_b32_e32 v20, v193
	v_mov_b32_e32 v21, v195
	v_pk_fma_f32 v[24:25], v[24:25], v[22:23], v[20:21]
	s_andn2_b64 exec, exec, s[12:13]
	s_cbranch_execnz .LBB0_1345
	s_or_b64 exec, exec, s[12:13]

; DI float bflo(unsigned w) { return __uint_as_float(w << 16); }
; DI float bfhi(unsigned w) { return __uint_as_float(w & 0xffff0000u); }
; DI unsigned pk2(float lo, float hi) { return pg8::cvt_pk_bf16(lo, hi); }
; DI void lru_pass3(const Ctx& C, const bf16* LA, const bf16* BV, const f32x2* AGG, const bf16* PROJ, float* HT, bf16* YMIX) {
;     ...
;         const size_t tok0 = (size_t)b * SEQ + seg * LSEG; const bf16* la0 = LA + tok0 * 1024 + ch; const bf16* bv0 = BV + tok0 * 1024 + ch; bf16* yp = YMIX + tok0 * D + ch;
; #pragma unroll 16
;         for (int i = 0; i < LSEG; ++i) { const unsigned lw = *(const unsigned*)(la0 + i * 1024), bw = *(const unsigned*)(bv0 + i * 1024);
;             h0 = __expf(bflo(lw)) * h0 + bflo(bw); h1 = __expf(bfhi(lw)) * h1 + bfhi(bw); *(unsigned*)(yp + i * D) = pk2(h0, h1); }
.LBB0_1352:
	s_andn2_saveexec_b64 s[8:9], s[8:9]
	v_mov_b32_e32 v24, 0
	v_mov_b32_e32 v25, v24
	s_or_b64 exec, exec, s[8:9]
	v_ashrrev_i32_e32 v11, 31, v10
	v_and_b32_e32 v14, 63, v13
	v_lshlrev_b64 v[6:7], 24, v[10:11]
	v_lshlrev_b64 v[8:9], 25, v[10:11]
	v_lshl_or_b32 v6, v14, 18, v6
	v_lshl_or_b32 v8, v14, 19, v8
	v_lshl_add_u64 v[6:7], s[72:73], 0, v[6:7]
	v_lshl_add_u64 v[8:9], s[72:73], 0, v[8:9]
	v_lshlrev_b32_e32 v2, 1, v12
	s_movk_i32 s8, 0x80
	v_mov_b64_e32 v[16:17], v[8:9]
	v_mov_b64_e32 v[18:19], v[6:7]
	s_mov_b64 s[10:11], 0x8000
	s_mov_b64 s[12:13], 0x10000
	v_lshl_add_u64 v[40:41], v[18:19], 0, v[2:3]
	v_add_co_u32_e32 v40, vcc, 0x1f000000, v40
	s_nop 1
	v_addc_co_u32_e32 v41, vcc, 0, v41, vcc
	v_add_co_u32_e32 v42, vcc, 0x4000000, v40
	s_nop 1
	v_addc_co_u32_e32 v43, vcc, 0, v41, vcc
	v_lshl_add_u64 v[44:45], v[16:17], 0, v[2:3]
	v_add_co_u32_e32 v44, vcc, s82, v44
	s_nop 1
	v_addc_co_u32_e32 v45, vcc, 0, v45, vcc
.LBB0_1355:
	global_load_dword v100, v[40:41], off
	global_load_dword v101, v[40:41], off offset:2048
	global_load_dword v124, v[42:43], off
	global_load_dword v125, v[42:43], off offset:2048
	v_lshl_add_u64 v[40:41], v[40:41], 0, v[46:47]
	v_lshl_add_u64 v[42:43], v[42:43], 0, v[46:47]
	global_load_dword v102, v[40:41], off
	global_load_dword v103, v[40:41], off offset:2048
	global_load_dword v126, v[42:43], off
	global_load_dword v127, v[42:43], off offset:2048
	v_lshl_add_u64 v[40:41], v[40:41], 0, v[46:47]
	v_lshl_add_u64 v[42:43], v[42:43], 0, v[46:47]
	global_load_dword v104, v[40:41], off
	global_load_dword v105, v[40:41], off offset:2048
	global_load_dword v128, v[42:43], off
	global_load_dword v129, v[42:43], off offset:2048
	v_lshl_add_u64 v[40:41], v[40:41], 0, v[46:47]
	v_lshl_add_u64 v[42:43], v[42:43], 0, v[46:47]
	global_load_dword v106, v[40:41], off
	global_load_dword v107, v[40:41], off offset:2048
	global_load_dword v130, v[42:43], off
	global_load_dword v131, v[42:43], off offset:2048
	v_lshl_add_u64 v[40:41], v[40:41], 0, v[46:47]
	v_lshl_add_u64 v[42:43], v[42:43], 0, v[46:47]
	global_load_dword v108, v[40:41], off
	global_load_dword v109, v[40:41], off offset:2048
	global_load_dword v132, v[42:43], off
	global_load_dword v133, v[42:43], off offset:2048
	v_lshl_add_u64 v[40:41], v[40:41], 0, v[46:47]
	v_lshl_add_u64 v[42:43], v[42:43], 0, v[46:47]
	global_load_dword v110, v[40:41], off
	global_load_dword v111, v[40:41], off offset:2048
	global_load_dword v134, v[42:43], off
	global_load_dword v135, v[42:43], off offset:2048
	v_lshl_add_u64 v[40:41], v[40:41], 0, v[46:47]
	v_lshl_add_u64 v[42:43], v[42:43], 0, v[46:47]
	global_load_dword v112, v[40:41], off
	global_load_dword v113, v[40:41], off offset:2048
	global_load_dword v136, v[42:43], off
	global_load_dword v137, v[42:43], off offset:2048
	v_lshl_add_u64 v[40:41], v[40:41], 0, v[46:47]
	v_lshl_add_u64 v[42:43], v[42:43], 0, v[46:47]
	global_load_dword v114, v[40:41], off
	global_load_dword v115, v[40:41], off offset:2048
	global_load_dword v138, v[42:43], off
	global_load_dword v139, v[42:43], off offset:2048
	v_lshl_add_u64 v[40:41], v[40:41], 0, v[46:47]
	v_lshl_add_u64 v[42:43], v[42:43], 0, v[46:47]
	s_waitcnt vmcnt(29) lgkmcnt(0)
	v_lshlrev_b32_e32 v20, 16, v100
	v_and_b32_e32 v21, 0xffff0000, v100
	v_mul_f32_e32 v20, 0x3fb8aa3b, v20
	v_mul_f32_e32 v21, 0x3fb8aa3b, v21
	v_exp_f32_e32 v20, v20
	v_exp_f32_e32 v21, v21
	v_lshlrev_b32_e32 v22, 16, v124
	v_and_b32_e32 v23, 0xffff0000, v124
	v_pk_fma_f32 v[24:25], v[24:25], v[20:21], v[22:23]
	s_nop 0
	v_cvt_pk_bf16_f32 v11, v24, v25
	global_store_dword v[44:45], v11, off
	v_lshl_add_u64 v[44:45], v[44:45], 0, v[46:47]
	s_waitcnt vmcnt(29)
	v_lshlrev_b32_e32 v20, 16, v101
	v_and_b32_e32 v21, 0xffff0000, v101
	v_mul_f32_e32 v20, 0x3fb8aa3b, v20
	v_mul_f32_e32 v21, 0x3fb8aa3b, v21
	v_exp_f32_e32 v20, v20
	v_exp_f32_e32 v21, v21
	v_lshlrev_b32_e32 v22, 16, v125
	v_and_b32_e32 v23, 0xffff0000, v125
	v_pk_fma_f32 v[24:25], v[24:25], v[20:21], v[22:23]
	s_nop 0
	v_cvt_pk_bf16_f32 v11, v24, v25
	global_store_dword v[44:45], v11, off
	v_lshl_add_u64 v[44:45], v[44:45], 0, v[46:47]
	s_waitcnt vmcnt(27)
	v_lshlrev_b32_e32 v20, 16, v102
	v_and_b32_e32 v21, 0xffff0000, v102
	v_mul_f32_e32 v20, 0x3fb8aa3b, v20
	v_mul_f32_e32 v21, 0x3fb8aa3b, v21
	v_exp_f32_e32 v20, v20
	v_exp_f32_e32 v21, v21
	v_lshlrev_b32_e32 v22, 16, v126
	v_and_b32_e32 v23, 0xffff0000, v126
	v_pk_fma_f32 v[24:25], v[24:25], v[20:21], v[22:23]
	s_nop 0
	v_cvt_pk_bf16_f32 v11, v24, v25
	global_store_dword v[44:45], v11, off
	v_lshl_add_u64 v[44:45], v[44:45], 0, v[46:47]
	s_waitcnt vmcnt(27)
	v_lshlrev_b32_e32 v20, 16, v103
	v_and_b32_e32 v21, 0xffff0000, v103
	v_mul_f32_e32 v20, 0x3fb8aa3b, v20
	v_mul_f32_e32 v21, 0x3fb8aa3b, v21
	v_exp_f32_e32 v20, v20
	v_exp_f32_e32 v21, v21
	v_lshlrev_b32_e32 v22, 16, v127
	v_and_b32_e32 v23, 0xffff0000, v127
	v_pk_fma_f32 v[24:25], v[24:25], v[20:21], v[22:23]
	s_nop 0
	v_cvt_pk_bf16_f32 v11, v24, v25
	global_store_dword v[44:45], v11, off
	v_lshl_add_u64 v[44:45], v[44:45], 0, v[46:47]
	s_waitcnt vmcnt(25)
	v_lshlrev_b32_e32 v20, 16, v104
	v_and_b32_e32 v21, 0xffff0000, v104
	v_mul_f32_e32 v20, 0x3fb8aa3b, v20
	v_mul_f32_e32 v21, 0x3fb8aa3b, v21
	v_exp_f32_e32 v20, v20
	v_exp_f32_e32 v21, v21
	v_lshlrev_b32_e32 v22, 16, v128
	v_and_b32_e32 v23, 0xffff0000, v128
	v_pk_fma_f32 v[24:25], v[24:25], v[20:21], v[22:23]
	s_nop 0
	v_cvt_pk_bf16_f32 v11, v24, v25
	global_store_dword v[44:45], v11, off
	v_lshl_add_u64 v[44:45], v[44:45], 0, v[46:47]
	s_waitcnt vmcnt(25)
; DI float bflo(unsigned w) { return __uint_as_float(w << 16); }
; DI float bfhi(unsigned w) { return __uint_as_float(w & 0xffff0000u); }
; DI unsigned pk2(float lo, float hi) { return pg8::cvt_pk_bf16(lo, hi); }
; DI void lru_pass3(const Ctx& C, const bf16* LA, const bf16* BV, const f32x2* AGG, const bf16* PROJ, float* HT, bf16* YMIX) {
;     ...
;         for (int i = 0; i < LSEG; ++i) { const unsigned lw = *(const unsigned*)(la0 + i * 1024), bw = *(const unsigned*)(bv0 + i * 1024);
;             h0 = __expf(bflo(lw)) * h0 + bflo(bw); h1 = __expf(bfhi(lw)) * h1 + bfhi(bw); *(unsigned*)(yp + i * D) = pk2(h0, h1); }
;         h0 = 0.f; h1 = 0.f;
; #pragma unroll 8
;         for (int s = 0; s < LNSEG - 1 - seg; ++s) { const f32x4 e = *(const f32x4*)(AGG + ((size_t)((b * 2 + 1) * LNSEG + s)) * 1024 + ch); h0 = e.x * h0 + e.y; h1 = e.z * h1 + e.w; }
	v_lshlrev_b32_e32 v20, 16, v105
	v_and_b32_e32 v21, 0xffff0000, v105
	v_mul_f32_e32 v20, 0x3fb8aa3b, v20
	v_mul_f32_e32 v21, 0x3fb8aa3b, v21
	v_exp_f32_e32 v20, v20
	v_exp_f32_e32 v21, v21
	v_lshlrev_b32_e32 v22, 16, v129
	v_and_b32_e32 v23, 0xffff0000, v129
	v_pk_fma_f32 v[24:25], v[24:25], v[20:21], v[22:23]
	s_nop 0
	v_cvt_pk_bf16_f32 v11, v24, v25
	global_store_dword v[44:45], v11, off
	v_lshl_add_u64 v[44:45], v[44:45], 0, v[46:47]
	s_waitcnt vmcnt(23)
	v_lshlrev_b32_e32 v20, 16, v106
	v_and_b32_e32 v21, 0xffff0000, v106
	v_mul_f32_e32 v20, 0x3fb8aa3b, v20
	v_mul_f32_e32 v21, 0x3fb8aa3b, v21
	v_exp_f32_e32 v20, v20
	v_exp_f32_e32 v21, v21
	v_lshlrev_b32_e32 v22, 16, v130
	v_and_b32_e32 v23, 0xffff0000, v130
	v_pk_fma_f32 v[24:25], v[24:25], v[20:21], v[22:23]
	s_nop 0
	v_cvt_pk_bf16_f32 v11, v24, v25
	global_store_dword v[44:45], v11, off
	v_lshl_add_u64 v[44:45], v[44:45], 0, v[46:47]
	s_waitcnt vmcnt(23)
	v_lshlrev_b32_e32 v20, 16, v107
	v_and_b32_e32 v21, 0xffff0000, v107
	v_mul_f32_e32 v20, 0x3fb8aa3b, v20
	v_mul_f32_e32 v21, 0x3fb8aa3b, v21
	v_exp_f32_e32 v20, v20
	v_exp_f32_e32 v21, v21
	v_lshlrev_b32_e32 v22, 16, v131
	v_and_b32_e32 v23, 0xffff0000, v131
	v_pk_fma_f32 v[24:25], v[24:25], v[20:21], v[22:23]
	s_nop 0
	v_cvt_pk_bf16_f32 v11, v24, v25
	global_store_dword v[44:45], v11, off
	v_lshl_add_u64 v[44:45], v[44:45], 0, v[46:47]
	s_waitcnt vmcnt(21)
	v_lshlrev_b32_e32 v20, 16, v108
	v_and_b32_e32 v21, 0xffff0000, v108
	v_mul_f32_e32 v20, 0x3fb8aa3b, v20
	v_mul_f32_e32 v21, 0x3fb8aa3b, v21
	v_exp_f32_e32 v20, v20
	v_exp_f32_e32 v21, v21
	v_lshlrev_b32_e32 v22, 16, v132
	v_and_b32_e32 v23, 0xffff0000, v132
	v_pk_fma_f32 v[24:25], v[24:25], v[20:21], v[22:23]
	s_nop 0
	v_cvt_pk_bf16_f32 v11, v24, v25
	global_store_dword v[44:45], v11, off
	v_lshl_add_u64 v[44:45], v[44:45], 0, v[46:47]
	s_waitcnt vmcnt(21)
	v_lshlrev_b32_e32 v20, 16, v109
	v_and_b32_e32 v21, 0xffff0000, v109
	v_mul_f32_e32 v20, 0x3fb8aa3b, v20
	v_mul_f32_e32 v21, 0x3fb8aa3b, v21
	v_exp_f32_e32 v20, v20
	v_exp_f32_e32 v21, v21
	v_lshlrev_b32_e32 v22, 16, v133
	v_and_b32_e32 v23, 0xffff0000, v133
	v_pk_fma_f32 v[24:25], v[24:25], v[20:21], v[22:23]
	s_nop 0
	v_cvt_pk_bf16_f32 v11, v24, v25
	global_store_dword v[44:45], v11, off
	v_lshl_add_u64 v[44:45], v[44:45], 0, v[46:47]
	s_waitcnt vmcnt(19)
	v_lshlrev_b32_e32 v20, 16, v110
	v_and_b32_e32 v21, 0xffff0000, v110
	v_mul_f32_e32 v20, 0x3fb8aa3b, v20
	v_mul_f32_e32 v21, 0x3fb8aa3b, v21
	v_exp_f32_e32 v20, v20
	v_exp_f32_e32 v21, v21
	v_lshlrev_b32_e32 v22, 16, v134
	v_and_b32_e32 v23, 0xffff0000, v134
	v_pk_fma_f32 v[24:25], v[24:25], v[20:21], v[22:23]
	s_nop 0
	v_cvt_pk_bf16_f32 v11, v24, v25
	global_store_dword v[44:45], v11, off
	v_lshl_add_u64 v[44:45], v[44:45], 0, v[46:47]
	s_waitcnt vmcnt(19)
	v_lshlrev_b32_e32 v20, 16, v111
	v_and_b32_e32 v21, 0xffff0000, v111
	v_mul_f32_e32 v20, 0x3fb8aa3b, v20
	v_mul_f32_e32 v21, 0x3fb8aa3b, v21
	v_exp_f32_e32 v20, v20
	v_exp_f32_e32 v21, v21
	v_lshlrev_b32_e32 v22, 16, v135
	v_and_b32_e32 v23, 0xffff0000, v135
	v_pk_fma_f32 v[24:25], v[24:25], v[20:21], v[22:23]
	s_nop 0
	v_cvt_pk_bf16_f32 v11, v24, v25
	global_store_dword v[44:45], v11, off
	v_lshl_add_u64 v[44:45], v[44:45], 0, v[46:47]
	s_waitcnt vmcnt(17)
	v_lshlrev_b32_e32 v20, 16, v112
	v_and_b32_e32 v21, 0xffff0000, v112
	v_mul_f32_e32 v20, 0x3fb8aa3b, v20
	v_mul_f32_e32 v21, 0x3fb8aa3b, v21
	v_exp_f32_e32 v20, v20
	v_exp_f32_e32 v21, v21
	v_lshlrev_b32_e32 v22, 16, v136
	v_and_b32_e32 v23, 0xffff0000, v136
	v_pk_fma_f32 v[24:25], v[24:25], v[20:21], v[22:23]
	s_nop 0
	v_cvt_pk_bf16_f32 v11, v24, v25
	global_store_dword v[44:45], v11, off
	v_lshl_add_u64 v[44:45], v[44:45], 0, v[46:47]
	s_waitcnt vmcnt(17)
	v_lshlrev_b32_e32 v20, 16, v113
	v_and_b32_e32 v21, 0xffff0000, v113
	v_mul_f32_e32 v20, 0x3fb8aa3b, v20
	v_mul_f32_e32 v21, 0x3fb8aa3b, v21
	v_exp_f32_e32 v20, v20
	v_exp_f32_e32 v21, v21
	v_lshlrev_b32_e32 v22, 16, v137
	v_and_b32_e32 v23, 0xffff0000, v137
	v_pk_fma_f32 v[24:25], v[24:25], v[20:21], v[22:23]
	s_nop 0
	v_cvt_pk_bf16_f32 v11, v24, v25
	global_store_dword v[44:45], v11, off
	v_lshl_add_u64 v[44:45], v[44:45], 0, v[46:47]
	s_waitcnt vmcnt(15)
	v_lshlrev_b32_e32 v20, 16, v114
	v_and_b32_e32 v21, 0xffff0000, v114
	v_mul_f32_e32 v20, 0x3fb8aa3b, v20
	v_mul_f32_e32 v21, 0x3fb8aa3b, v21
	v_exp_f32_e32 v20, v20
	v_exp_f32_e32 v21, v21
	v_lshlrev_b32_e32 v22, 16, v138
	v_and_b32_e32 v23, 0xffff0000, v138
	v_pk_fma_f32 v[24:25], v[24:25], v[20:21], v[22:23]
	s_nop 0
	v_cvt_pk_bf16_f32 v11, v24, v25
	global_store_dword v[44:45], v11, off
	v_lshl_add_u64 v[44:45], v[44:45], 0, v[46:47]
	s_waitcnt vmcnt(15)
	v_lshlrev_b32_e32 v20, 16, v115
	v_and_b32_e32 v21, 0xffff0000, v115
	v_mul_f32_e32 v20, 0x3fb8aa3b, v20
	v_mul_f32_e32 v21, 0x3fb8aa3b, v21
	v_exp_f32_e32 v20, v20
	v_exp_f32_e32 v21, v21
	v_lshlrev_b32_e32 v22, 16, v139
	v_and_b32_e32 v23, 0xffff0000, v139
	v_pk_fma_f32 v[24:25], v[24:25], v[20:21], v[22:23]
	s_nop 0
	v_cvt_pk_bf16_f32 v11, v24, v25
	global_store_dword v[44:45], v11, off
	v_lshl_add_u64 v[44:45], v[44:45], 0, v[46:47]
	s_add_i32 s8, s8, -16
	s_cmp_eq_u32 s8, 0
	s_cbranch_scc0 .LBB0_1355
	v_mov_b32_e32 v19, 0
	v_cmp_ne_u32_e32 vcc, 63, v29
	v_mov_b32_e32 v18, v19
	s_and_saveexec_b64 s[8:9], vcc
	s_cbranch_execz .LBB0_1366
	v_xor_b32_e32 v11, 63, v29
	v_xor_b32_e32 v20, 63, v13
	v_lshlrev_b32_e32 v16, 7, v10
	v_cmp_lt_u32_e32 vcc, 7, v11
	v_mov_b32_e32 v18, v3
	v_mov_b32_e32 v19, v3
	v_mov_b32_e32 v13, 0
	s_and_saveexec_b64 s[10:11], vcc
	s_cbranch_execz .LBB0_1361
	v_and_b32_e32 v18, 63, v20
	v_mov_b32_e32 v19, v3
	v_cmp_lt_u64_e32 vcc, 1, v[18:19]
	v_ashrrev_i32_e32 v17, 31, v16
	s_mov_b32 s16, 0
	v_cndmask_b32_e32 v13, 1, v18, vcc
	v_lshlrev_b64 v[18:19], 13, v[16:17]
	v_lshl_or_b32 v18, v12, 3, v18
	v_lshlrev_b32_e32 v13, 13, v13
	v_lshl_add_u64 v[24:25], s[72:73], 0, v[18:19]
	v_mov_b32_e32 v18, 0
	v_and_b32_e32 v22, 0x70000, v13
	s_mov_b64 s[12:13], 0
	s_mov_b64 s[14:15], 0
	v_mov_b32_e32 v19, v18
; DI void lru_pass3(const Ctx& C, const bf16* LA, const bf16* BV, const f32x2* AGG, const bf16* PROJ, float* HT, bf16* YMIX) {
;     ...
; #pragma unroll 8
;         for (int s = 0; s < LNSEG - 1 - seg; ++s) { const f32x4 e = *(const f32x4*)(AGG + ((size_t)((b * 2 + 1) * LNSEG + s)) * 1024 + ch); h0 = e.x * h0 + e.y; h1 = e.z * h1 + e.w; }
.LBB0_1359:
	v_lshl_add_u64 v[26:27], v[24:25], 0, s[14:15]
	v_add_co_u32_e32 v30, vcc, 0x380000, v26
	s_add_i32 s16, s16, 8
	s_nop 0
	v_addc_co_u32_e32 v31, vcc, 0, v27, vcc
	global_load_dwordx4 v[164:167], v[30:31], off
	v_lshl_add_u64 v[30:31], v[30:31], 0, v[48:49]
	global_load_dwordx4 v[168:171], v[30:31], off
	v_lshl_add_u64 v[30:31], v[30:31], 0, v[48:49]
	global_load_dwordx4 v[172:175], v[30:31], off
	v_lshl_add_u64 v[30:31], v[30:31], 0, v[48:49]
	global_load_dwordx4 v[176:179], v[30:31], off
	v_lshl_add_u64 v[30:31], v[30:31], 0, v[48:49]
	global_load_dwordx4 v[180:183], v[30:31], off
	v_lshl_add_u64 v[30:31], v[30:31], 0, v[48:49]
	global_load_dwordx4 v[184:187], v[30:31], off
	v_lshl_add_u64 v[30:31], v[30:31], 0, v[48:49]
	global_load_dwordx4 v[188:191], v[30:31], off
	v_lshl_add_u64 v[30:31], v[30:31], 0, v[48:49]
	global_load_dwordx4 v[192:195], v[30:31], off
	v_lshl_add_u64 v[30:31], v[30:31], 0, v[48:49]
	s_add_u32 s14, s14, 0x10000
	s_addc_u32 s15, s15, 0
	v_mov_b32_e32 v13, s16
	v_cmp_eq_u32_e32 vcc, s14, v22
	s_or_b64 s[12:13], vcc, s[12:13]
	s_waitcnt vmcnt(7) lgkmcnt(0)
	v_mov_b32_e32 v34, v164
	v_mov_b32_e32 v35, v166
	v_mov_b32_e32 v32, v165
	v_mov_b32_e32 v33, v167
	v_pk_fma_f32 v[18:19], v[18:19], v[34:35], v[32:33]
	s_waitcnt vmcnt(6)
	v_mov_b32_e32 v34, v168
	v_mov_b32_e32 v35, v170
	v_mov_b32_e32 v32, v169
	v_mov_b32_e32 v33, v171
	v_pk_fma_f32 v[18:19], v[18:19], v[34:35], v[32:33]
	s_waitcnt vmcnt(5)
	v_mov_b32_e32 v34, v172
	v_mov_b32_e32 v35, v174
	v_mov_b32_e32 v32, v173
	v_mov_b32_e32 v33, v175
	v_pk_fma_f32 v[18:19], v[18:19], v[34:35], v[32:33]
	s_waitcnt vmcnt(4)
	v_mov_b32_e32 v34, v176
	v_mov_b32_e32 v35, v178
	v_mov_b32_e32 v32, v177
	v_mov_b32_e32 v33, v179
	v_pk_fma_f32 v[18:19], v[18:19], v[34:35], v[32:33]
	s_waitcnt vmcnt(3)
	v_mov_b32_e32 v34, v180
	v_mov_b32_e32 v35, v182
	v_mov_b32_e32 v32, v181
	v_mov_b32_e32 v33, v183
	v_pk_fma_f32 v[18:19], v[18:19], v[34:35], v[32:33]
	s_waitcnt vmcnt(2)
	v_mov_b32_e32 v34, v184
	v_mov_b32_e32 v35, v186
	v_mov_b32_e32 v32, v185
	v_mov_b32_e32 v33, v187
	v_pk_fma_f32 v[18:19], v[18:19], v[34:35], v[32:33]
	s_waitcnt vmcnt(1)
	v_mov_b32_e32 v34, v188
	v_mov_b32_e32 v35, v190
	v_mov_b32_e32 v32, v189
	v_mov_b32_e32 v33, v191
	v_pk_fma_f32 v[18:19], v[18:19], v[34:35], v[32:33]
	s_waitcnt vmcnt(0)
	v_mov_b32_e32 v34, v192
	v_mov_b32_e32 v35, v194
	v_mov_b32_e32 v32, v193
	v_mov_b32_e32 v33, v195
	v_pk_fma_f32 v[18:19], v[18:19], v[34:35], v[32:33]
	s_andn2_b64 exec, exec, s[12:13]
	s_cbranch_execnz .LBB0_1359
	s_or_b64 exec, exec, s[12:13]

; DI float bflo(unsigned w) { return __uint_as_float(w << 16); }
; DI float bfhi(unsigned w) { return __uint_as_float(w & 0xffff0000u); }
; DI unsigned pk2(float lo, float hi) { return pg8::cvt_pk_bf16(lo, hi); }
; DI float gelu_tanh(float x) { const float u = 0.7978845608028654f * (x + 0.044715f * x * x * x); return x * sigm(2.0f * u); }
; DI void lru_pass3(const Ctx& C, const bf16* LA, const bf16* BV, const f32x2* AGG, const bf16* PROJ, float* HT, bf16* YMIX) {
;     ...
;         const bf16* la1 = la0 + (size_t)T * 1024; const bf16* bv1 = bv0 + (size_t)T * 1024; const bf16* gp = PROJ + tok0 * AB_N + 1024 + ch;
; #pragma unroll 16
;         for (int i = LSEG - 1; i >= 0; --i) { const unsigned lw = *(const unsigned*)(la1 + i * 1024), bw = *(const unsigned*)(bv1 + i * 1024), gw = *(const unsigned*)(gp + (size_t)i * AB_N), fw = *(const unsigned*)(yp + i * D);
;             h0 = __expf(bflo(lw)) * h0 + bflo(bw); h1 = __expf(bfhi(lw)) * h1 + bfhi(bw);
;             *(unsigned*)(yp + i * D) = pk2(gelu_tanh(bflo(gw)) * (bflo(fw) + h0), gelu_tanh(bfhi(gw)) * (bfhi(fw) + h1)); }
.LBB0_1366:
	s_or_b64 exec, exec, s[8:9]
	v_mul_hi_u32_u24_e32 v13, 0x180000, v14
	v_mul_u32_u24_e32 v12, 0x180000, v14
	s_mov_b32 s8, 0x6000000
	v_mad_i64_i32 v[10:11], s[8:9], v10, s8, v[12:13]
	v_lshl_add_u64 v[10:11], s[72:73], 0, v[10:11]
	s_movk_i32 s8, 0xff80
	v_lshl_add_u64 v[40:41], v[6:7], 0, v[2:3]
	v_add_co_u32_e32 v40, vcc, 0x2103f800, v40
	s_nop 1
	v_addc_co_u32_e32 v41, vcc, 0, v41, vcc
	v_add_co_u32_e32 v42, vcc, 0x4000000, v40
	s_nop 1
	v_addc_co_u32_e32 v43, vcc, 0, v41, vcc
	v_lshl_add_u64 v[36:37], v[10:11], 0, v[2:3]
	v_add_co_u32_e32 v36, vcc, 0x1317d800, v36
	s_nop 1
	v_addc_co_u32_e32 v37, vcc, 0, v37, vcc
	v_lshl_add_u64 v[44:45], v[8:9], 0, v[2:3]
	v_add_co_u32_e32 v44, vcc, 0xf07f000, v44
	s_nop 1
	v_addc_co_u32_e32 v45, vcc, 0, v45, vcc
	v_lshl_add_u64 v[38:39], v[44:45], 0, 0
	v_mov_b32_e32 v50, 0xfffff000
	v_mov_b32_e32 v51, -1
	v_mov_b32_e32 v52, 0xffffd000
	v_mov_b32_e32 v53, -1
	v_mov_b32_e32 v54, 0xffffe000
	v_mov_b32_e32 v55, -1
.LBB0_1367:
	global_load_dword v100, v[40:41], off
	global_load_dword v101, v[40:41], off offset:-2048
	global_load_dword v108, v[42:43], off
	global_load_dword v109, v[42:43], off offset:-2048
	global_load_dword v124, v[36:37], off
	v_lshl_add_u64 v[36:37], v[36:37], 0, v[52:53]
	global_load_dword v125, v[36:37], off
	v_lshl_add_u64 v[36:37], v[36:37], 0, v[52:53]
	global_load_dword v132, v[38:39], off
	global_load_dword v133, v[38:39], off offset:-4096
	v_lshl_add_u64 v[40:41], v[40:41], 0, v[50:51]
	v_lshl_add_u64 v[42:43], v[42:43], 0, v[50:51]
	v_lshl_add_u64 v[38:39], v[38:39], 0, v[54:55]
	global_load_dword v102, v[40:41], off
	global_load_dword v103, v[40:41], off offset:-2048
	global_load_dword v110, v[42:43], off
	global_load_dword v111, v[42:43], off offset:-2048
	global_load_dword v126, v[36:37], off
	v_lshl_add_u64 v[36:37], v[36:37], 0, v[52:53]
	global_load_dword v127, v[36:37], off
	v_lshl_add_u64 v[36:37], v[36:37], 0, v[52:53]
	global_load_dword v134, v[38:39], off
	global_load_dword v135, v[38:39], off offset:-4096
	v_lshl_add_u64 v[40:41], v[40:41], 0, v[50:51]
	v_lshl_add_u64 v[42:43], v[42:43], 0, v[50:51]
	v_lshl_add_u64 v[38:39], v[38:39], 0, v[54:55]
	global_load_dword v104, v[40:41], off
	global_load_dword v105, v[40:41], off offset:-2048
	global_load_dword v112, v[42:43], off
	global_load_dword v113, v[42:43], off offset:-2048
	global_load_dword v128, v[36:37], off
	v_lshl_add_u64 v[36:37], v[36:37], 0, v[52:53]
	global_load_dword v129, v[36:37], off
	v_lshl_add_u64 v[36:37], v[36:37], 0, v[52:53]
	global_load_dword v136, v[38:39], off
	global_load_dword v137, v[38:39], off offset:-4096
	v_lshl_add_u64 v[40:41], v[40:41], 0, v[50:51]
	v_lshl_add_u64 v[42:43], v[42:43], 0, v[50:51]
	v_lshl_add_u64 v[38:39], v[38:39], 0, v[54:55]
	global_load_dword v106, v[40:41], off
	global_load_dword v107, v[40:41], off offset:-2048
	global_load_dword v114, v[42:43], off
	global_load_dword v115, v[42:43], off offset:-2048
	global_load_dword v130, v[36:37], off
	v_lshl_add_u64 v[36:37], v[36:37], 0, v[52:53]
	global_load_dword v131, v[36:37], off
	v_lshl_add_u64 v[36:37], v[36:37], 0, v[52:53]
	global_load_dword v138, v[38:39], off
	global_load_dword v139, v[38:39], off offset:-4096
	v_lshl_add_u64 v[40:41], v[40:41], 0, v[50:51]
	v_lshl_add_u64 v[42:43], v[42:43], 0, v[50:51]
	v_lshl_add_u64 v[38:39], v[38:39], 0, v[54:55]
	s_waitcnt vmcnt(25) lgkmcnt(0)
	v_lshlrev_b32_e32 v26, 16, v100
	v_and_b32_e32 v27, 0xffff0000, v100
	v_mul_f32_e32 v26, 0x3fb8aa3b, v26
	v_mul_f32_e32 v27, 0x3fb8aa3b, v27
	v_exp_f32_e32 v26, v26
	v_exp_f32_e32 v27, v27
	v_lshlrev_b32_e32 v30, 16, v108
	v_and_b32_e32 v31, 0xffff0000, v108
	v_pk_fma_f32 v[18:19], v[18:19], v[26:27], v[30:31]
	v_lshlrev_b32_e32 v26, 16, v124
	v_mul_f32_e32 v29, 0x3d372713, v26
	v_and_b32_e32 v27, 0xffff0000, v124
	v_mul_f32_e32 v29, v29, v26
	v_mov_b32_e32 v32, v26
	v_fmac_f32_e32 v32, v29, v32
	v_mul_f32_e32 v29, 0x3f4c422a, v32
	v_add_f32_e32 v29, v29, v29
	v_mul_f32_e32 v29, 0xbfb8aa3b, v29
	v_exp_f32_e32 v29, v29
	v_lshlrev_b32_e32 v30, 16, v132
	v_and_b32_e32 v31, 0xffff0000, v132
	v_mov_b32_e32 v33, v27
	v_add_f32_e32 v29, 1.0, v29
	v_rcp_f32_e32 v32, v29
	v_mul_f32_e32 v29, 0x3d372713, v27
	v_mul_f32_e32 v29, v29, v27
	v_fmac_f32_e32 v33, v29, v33
	v_mul_f32_e32 v29, 0x3f4c422a, v33
	v_add_f32_e32 v29, v29, v29
	v_mul_f32_e32 v29, 0xbfb8aa3b, v29
	v_exp_f32_e32 v29, v29
	v_pk_add_f32 v[30:31], v[18:19], v[30:31]
	v_add_f32_e32 v29, 1.0, v29
	v_rcp_f32_e32 v33, v29
	s_nop 0
	v_pk_mul_f32 v[26:27], v[32:33], v[26:27]
	s_nop 0
	v_pk_mul_f32 v[26:27], v[30:31], v[26:27]
	s_nop 0
	v_cvt_pk_bf16_f32 v26, v26, v27
	global_store_dword v[44:45], v26, off
	v_lshl_add_u64 v[44:45], v[44:45], 0, v[50:51]
	s_waitcnt vmcnt(25)
	v_lshlrev_b32_e32 v26, 16, v101
	v_and_b32_e32 v27, 0xffff0000, v101
	v_mul_f32_e32 v26, 0x3fb8aa3b, v26
	v_mul_f32_e32 v27, 0x3fb8aa3b, v27
	v_exp_f32_e32 v26, v26
	v_exp_f32_e32 v27, v27
	v_lshlrev_b32_e32 v30, 16, v109
	v_and_b32_e32 v31, 0xffff0000, v109
	v_pk_fma_f32 v[18:19], v[18:19], v[26:27], v[30:31]
	v_lshlrev_b32_e32 v26, 16, v125
	v_mul_f32_e32 v29, 0x3d372713, v26
	v_and_b32_e32 v27, 0xffff0000, v125
	v_mul_f32_e32 v29, v29, v26
	v_mov_b32_e32 v32, v26
	v_fmac_f32_e32 v32, v29, v32
	v_mul_f32_e32 v29, 0x3f4c422a, v32
	v_add_f32_e32 v29, v29, v29
	v_mul_f32_e32 v29, 0xbfb8aa3b, v29
	v_exp_f32_e32 v29, v29
	v_lshlrev_b32_e32 v30, 16, v133
	v_and_b32_e32 v31, 0xffff0000, v133
	v_mov_b32_e32 v33, v27
	v_add_f32_e32 v29, 1.0, v29
	v_rcp_f32_e32 v32, v29
	v_mul_f32_e32 v29, 0x3d372713, v27
	v_mul_f32_e32 v29, v29, v27
	v_fmac_f32_e32 v33, v29, v33
	v_mul_f32_e32 v29, 0x3f4c422a, v33
	v_add_f32_e32 v29, v29, v29
	v_mul_f32_e32 v29, 0xbfb8aa3b, v29
	v_exp_f32_e32 v29, v29
	v_pk_add_f32 v[30:31], v[18:19], v[30:31]
	v_add_f32_e32 v29, 1.0, v29
	v_rcp_f32_e32 v33, v29
	s_nop 0
	v_pk_mul_f32 v[26:27], v[32:33], v[26:27]
	s_nop 0
	v_pk_mul_f32 v[26:27], v[30:31], v[26:27]
	s_nop 0
	v_cvt_pk_bf16_f32 v26, v26, v27
	global_store_dword v[44:45], v26, off
	v_lshl_add_u64 v[44:45], v[44:45], 0, v[50:51]
	s_waitcnt vmcnt(19)
; DI float bflo(unsigned w) { return __uint_as_float(w << 16); }
; DI float bfhi(unsigned w) { return __uint_as_float(w & 0xffff0000u); }
; DI unsigned pk2(float lo, float hi) { return pg8::cvt_pk_bf16(lo, hi); }
; DI float gelu_tanh(float x) { const float u = 0.7978845608028654f * (x + 0.044715f * x * x * x); return x * sigm(2.0f * u); }
; DI void lru_pass3(const Ctx& C, const bf16* LA, const bf16* BV, const f32x2* AGG, const bf16* PROJ, float* HT, bf16* YMIX) {
;     ...
; #pragma unroll 16
;         for (int i = LSEG - 1; i >= 0; --i) { const unsigned lw = *(const unsigned*)(la1 + i * 1024), bw = *(const unsigned*)(bv1 + i * 1024), gw = *(const unsigned*)(gp + (size_t)i * AB_N), fw = *(const unsigned*)(yp + i * D);
;             h0 = __expf(bflo(lw)) * h0 + bflo(bw); h1 = __expf(bfhi(lw)) * h1 + bfhi(bw);
;             *(unsigned*)(yp + i * D) = pk2(gelu_tanh(bflo(gw)) * (bflo(fw) + h0), gelu_tanh(bfhi(gw)) * (bfhi(fw) + h1)); }
	v_lshlrev_b32_e32 v26, 16, v102
	v_and_b32_e32 v27, 0xffff0000, v102
	v_mul_f32_e32 v26, 0x3fb8aa3b, v26
	v_mul_f32_e32 v27, 0x3fb8aa3b, v27
	v_exp_f32_e32 v26, v26
	v_exp_f32_e32 v27, v27
	v_lshlrev_b32_e32 v30, 16, v110
	v_and_b32_e32 v31, 0xffff0000, v110
	v_pk_fma_f32 v[18:19], v[18:19], v[26:27], v[30:31]
	v_lshlrev_b32_e32 v26, 16, v126
	v_mul_f32_e32 v29, 0x3d372713, v26
	v_and_b32_e32 v27, 0xffff0000, v126
	v_mul_f32_e32 v29, v29, v26
	v_mov_b32_e32 v32, v26
	v_fmac_f32_e32 v32, v29, v32
	v_mul_f32_e32 v29, 0x3f4c422a, v32
	v_add_f32_e32 v29, v29, v29
	v_mul_f32_e32 v29, 0xbfb8aa3b, v29
	v_exp_f32_e32 v29, v29
	v_lshlrev_b32_e32 v30, 16, v134
	v_and_b32_e32 v31, 0xffff0000, v134
	v_mov_b32_e32 v33, v27
	v_add_f32_e32 v29, 1.0, v29
	v_rcp_f32_e32 v32, v29
	v_mul_f32_e32 v29, 0x3d372713, v27
	v_mul_f32_e32 v29, v29, v27
	v_fmac_f32_e32 v33, v29, v33
	v_mul_f32_e32 v29, 0x3f4c422a, v33
	v_add_f32_e32 v29, v29, v29
	v_mul_f32_e32 v29, 0xbfb8aa3b, v29
	v_exp_f32_e32 v29, v29
	v_pk_add_f32 v[30:31], v[18:19], v[30:31]
	v_add_f32_e32 v29, 1.0, v29
	v_rcp_f32_e32 v33, v29
	s_nop 0
	v_pk_mul_f32 v[26:27], v[32:33], v[26:27]
	s_nop 0
	v_pk_mul_f32 v[26:27], v[30:31], v[26:27]
	s_nop 0
	v_cvt_pk_bf16_f32 v26, v26, v27
	global_store_dword v[44:45], v26, off
	v_lshl_add_u64 v[44:45], v[44:45], 0, v[50:51]
	s_waitcnt vmcnt(19)
	v_lshlrev_b32_e32 v26, 16, v103
	v_and_b32_e32 v27, 0xffff0000, v103
	v_mul_f32_e32 v26, 0x3fb8aa3b, v26
	v_mul_f32_e32 v27, 0x3fb8aa3b, v27
	v_exp_f32_e32 v26, v26
	v_exp_f32_e32 v27, v27
	v_lshlrev_b32_e32 v30, 16, v111
	v_and_b32_e32 v31, 0xffff0000, v111
	v_pk_fma_f32 v[18:19], v[18:19], v[26:27], v[30:31]
	v_lshlrev_b32_e32 v26, 16, v127
	v_mul_f32_e32 v29, 0x3d372713, v26
	v_and_b32_e32 v27, 0xffff0000, v127
	v_mul_f32_e32 v29, v29, v26
	v_mov_b32_e32 v32, v26
	v_fmac_f32_e32 v32, v29, v32
	v_mul_f32_e32 v29, 0x3f4c422a, v32
	v_add_f32_e32 v29, v29, v29
	v_mul_f32_e32 v29, 0xbfb8aa3b, v29
	v_exp_f32_e32 v29, v29
	v_lshlrev_b32_e32 v30, 16, v135
	v_and_b32_e32 v31, 0xffff0000, v135
	v_mov_b32_e32 v33, v27
	v_add_f32_e32 v29, 1.0, v29
	v_rcp_f32_e32 v32, v29
	v_mul_f32_e32 v29, 0x3d372713, v27
	v_mul_f32_e32 v29, v29, v27
	v_fmac_f32_e32 v33, v29, v33
	v_mul_f32_e32 v29, 0x3f4c422a, v33
	v_add_f32_e32 v29, v29, v29
	v_mul_f32_e32 v29, 0xbfb8aa3b, v29
	v_exp_f32_e32 v29, v29
	v_pk_add_f32 v[30:31], v[18:19], v[30:31]
	v_add_f32_e32 v29, 1.0, v29
	v_rcp_f32_e32 v33, v29
	s_nop 0
	v_pk_mul_f32 v[26:27], v[32:33], v[26:27]
	s_nop 0
	v_pk_mul_f32 v[26:27], v[30:31], v[26:27]
	s_nop 0
	v_cvt_pk_bf16_f32 v26, v26, v27
	global_store_dword v[44:45], v26, off
	v_lshl_add_u64 v[44:45], v[44:45], 0, v[50:51]
	s_waitcnt vmcnt(13)
	v_lshlrev_b32_e32 v26, 16, v104
	v_and_b32_e32 v27, 0xffff0000, v104
	v_mul_f32_e32 v26, 0x3fb8aa3b, v26
	v_mul_f32_e32 v27, 0x3fb8aa3b, v27
	v_exp_f32_e32 v26, v26
	v_exp_f32_e32 v27, v27
	v_lshlrev_b32_e32 v30, 16, v112
	v_and_b32_e32 v31, 0xffff0000, v112
	v_pk_fma_f32 v[18:19], v[18:19], v[26:27], v[30:31]
	v_lshlrev_b32_e32 v26, 16, v128
	v_mul_f32_e32 v29, 0x3d372713, v26
	v_and_b32_e32 v27, 0xffff0000, v128
	v_mul_f32_e32 v29, v29, v26
	v_mov_b32_e32 v32, v26
	v_fmac_f32_e32 v32, v29, v32
	v_mul_f32_e32 v29, 0x3f4c422a, v32
	v_add_f32_e32 v29, v29, v29
	v_mul_f32_e32 v29, 0xbfb8aa3b, v29
	v_exp_f32_e32 v29, v29
	v_lshlrev_b32_e32 v30, 16, v136
	v_and_b32_e32 v31, 0xffff0000, v136
	v_mov_b32_e32 v33, v27
	v_add_f32_e32 v29, 1.0, v29
	v_rcp_f32_e32 v32, v29
	v_mul_f32_e32 v29, 0x3d372713, v27
	v_mul_f32_e32 v29, v29, v27
	v_fmac_f32_e32 v33, v29, v33
	v_mul_f32_e32 v29, 0x3f4c422a, v33
	v_add_f32_e32 v29, v29, v29
	v_mul_f32_e32 v29, 0xbfb8aa3b, v29
	v_exp_f32_e32 v29, v29
	v_pk_add_f32 v[30:31], v[18:19], v[30:31]
	v_add_f32_e32 v29, 1.0, v29
	v_rcp_f32_e32 v33, v29
	s_nop 0
	v_pk_mul_f32 v[26:27], v[32:33], v[26:27]
	s_nop 0
	v_pk_mul_f32 v[26:27], v[30:31], v[26:27]
	s_nop 0
	v_cvt_pk_bf16_f32 v26, v26, v27
	global_store_dword v[44:45], v26, off
	v_lshl_add_u64 v[44:45], v[44:45], 0, v[50:51]
	s_waitcnt vmcnt(13)
; DI float bflo(unsigned w) { return __uint_as_float(w << 16); }
; DI float bfhi(unsigned w) { return __uint_as_float(w & 0xffff0000u); }
; DI unsigned pk2(float lo, float hi) { return pg8::cvt_pk_bf16(lo, hi); }
; DI float gelu_tanh(float x) { const float u = 0.7978845608028654f * (x + 0.044715f * x * x * x); return x * sigm(2.0f * u); }
; DI void lru_pass3(const Ctx& C, const bf16* LA, const bf16* BV, const f32x2* AGG, const bf16* PROJ, float* HT, bf16* YMIX) {
;     ...
;     for (int idx = gt; idx < BATCH * LNSEG * 512; idx += ngt) {
;     ...
; #pragma unroll 16
;         for (int i = LSEG - 1; i >= 0; --i) { const unsigned lw = *(const unsigned*)(la1 + i * 1024), bw = *(const unsigned*)(bv1 + i * 1024), gw = *(const unsigned*)(gp + (size_t)i * AB_N), fw = *(const unsigned*)(yp + i * D);
;             h0 = __expf(bflo(lw)) * h0 + bflo(bw); h1 = __expf(bfhi(lw)) * h1 + bfhi(bw);
;             *(unsigned*)(yp + i * D) = pk2(gelu_tanh(bflo(gw)) * (bflo(fw) + h0), gelu_tanh(bfhi(gw)) * (bfhi(fw) + h1)); }
	v_lshlrev_b32_e32 v26, 16, v105
	v_and_b32_e32 v27, 0xffff0000, v105
	v_mul_f32_e32 v26, 0x3fb8aa3b, v26
	v_mul_f32_e32 v27, 0x3fb8aa3b, v27
	v_exp_f32_e32 v26, v26
	v_exp_f32_e32 v27, v27
	v_lshlrev_b32_e32 v30, 16, v113
	v_and_b32_e32 v31, 0xffff0000, v113
	v_pk_fma_f32 v[18:19], v[18:19], v[26:27], v[30:31]
	v_lshlrev_b32_e32 v26, 16, v129
	v_mul_f32_e32 v29, 0x3d372713, v26
	v_and_b32_e32 v27, 0xffff0000, v129
	v_mul_f32_e32 v29, v29, v26
	v_mov_b32_e32 v32, v26
	v_fmac_f32_e32 v32, v29, v32
	v_mul_f32_e32 v29, 0x3f4c422a, v32
	v_add_f32_e32 v29, v29, v29
	v_mul_f32_e32 v29, 0xbfb8aa3b, v29
	v_exp_f32_e32 v29, v29
	v_lshlrev_b32_e32 v30, 16, v137
	v_and_b32_e32 v31, 0xffff0000, v137
	v_mov_b32_e32 v33, v27
	v_add_f32_e32 v29, 1.0, v29
	v_rcp_f32_e32 v32, v29
	v_mul_f32_e32 v29, 0x3d372713, v27
	v_mul_f32_e32 v29, v29, v27
	v_fmac_f32_e32 v33, v29, v33
	v_mul_f32_e32 v29, 0x3f4c422a, v33
	v_add_f32_e32 v29, v29, v29
	v_mul_f32_e32 v29, 0xbfb8aa3b, v29
	v_exp_f32_e32 v29, v29
	v_pk_add_f32 v[30:31], v[18:19], v[30:31]
	v_add_f32_e32 v29, 1.0, v29
	v_rcp_f32_e32 v33, v29
	s_nop 0
	v_pk_mul_f32 v[26:27], v[32:33], v[26:27]
	s_nop 0
	v_pk_mul_f32 v[26:27], v[30:31], v[26:27]
	s_nop 0
	v_cvt_pk_bf16_f32 v26, v26, v27
	global_store_dword v[44:45], v26, off
	v_lshl_add_u64 v[44:45], v[44:45], 0, v[50:51]
	s_waitcnt vmcnt(7)
	v_lshlrev_b32_e32 v26, 16, v106
	v_and_b32_e32 v27, 0xffff0000, v106
	v_mul_f32_e32 v26, 0x3fb8aa3b, v26
	v_mul_f32_e32 v27, 0x3fb8aa3b, v27
	v_exp_f32_e32 v26, v26
	v_exp_f32_e32 v27, v27
	v_lshlrev_b32_e32 v30, 16, v114
	v_and_b32_e32 v31, 0xffff0000, v114
	v_pk_fma_f32 v[18:19], v[18:19], v[26:27], v[30:31]
	v_lshlrev_b32_e32 v26, 16, v130
	v_mul_f32_e32 v29, 0x3d372713, v26
	v_and_b32_e32 v27, 0xffff0000, v130
	v_mul_f32_e32 v29, v29, v26
	v_mov_b32_e32 v32, v26
	v_fmac_f32_e32 v32, v29, v32
	v_mul_f32_e32 v29, 0x3f4c422a, v32
	v_add_f32_e32 v29, v29, v29
	v_mul_f32_e32 v29, 0xbfb8aa3b, v29
	v_exp_f32_e32 v29, v29
	v_lshlrev_b32_e32 v30, 16, v138
	v_and_b32_e32 v31, 0xffff0000, v138
	v_mov_b32_e32 v33, v27
	v_add_f32_e32 v29, 1.0, v29
	v_rcp_f32_e32 v32, v29
	v_mul_f32_e32 v29, 0x3d372713, v27
	v_mul_f32_e32 v29, v29, v27
	v_fmac_f32_e32 v33, v29, v33
	v_mul_f32_e32 v29, 0x3f4c422a, v33
	v_add_f32_e32 v29, v29, v29
	v_mul_f32_e32 v29, 0xbfb8aa3b, v29
	v_exp_f32_e32 v29, v29
	v_pk_add_f32 v[30:31], v[18:19], v[30:31]
	v_add_f32_e32 v29, 1.0, v29
	v_rcp_f32_e32 v33, v29
	s_nop 0
	v_pk_mul_f32 v[26:27], v[32:33], v[26:27]
	s_nop 0
	v_pk_mul_f32 v[26:27], v[30:31], v[26:27]
	s_nop 0
	v_cvt_pk_bf16_f32 v26, v26, v27
	global_store_dword v[44:45], v26, off
	v_lshl_add_u64 v[44:45], v[44:45], 0, v[50:51]
	s_waitcnt vmcnt(7)
	v_lshlrev_b32_e32 v26, 16, v107
	v_and_b32_e32 v27, 0xffff0000, v107
	v_mul_f32_e32 v26, 0x3fb8aa3b, v26
	v_mul_f32_e32 v27, 0x3fb8aa3b, v27
	v_exp_f32_e32 v26, v26
	v_exp_f32_e32 v27, v27
	v_lshlrev_b32_e32 v30, 16, v115
	v_and_b32_e32 v31, 0xffff0000, v115
	v_pk_fma_f32 v[18:19], v[18:19], v[26:27], v[30:31]
	v_lshlrev_b32_e32 v26, 16, v131
	v_mul_f32_e32 v29, 0x3d372713, v26
	v_and_b32_e32 v27, 0xffff0000, v131
	v_mul_f32_e32 v29, v29, v26
	v_mov_b32_e32 v32, v26
	v_fmac_f32_e32 v32, v29, v32
	v_mul_f32_e32 v29, 0x3f4c422a, v32
	v_add_f32_e32 v29, v29, v29
	v_mul_f32_e32 v29, 0xbfb8aa3b, v29
	v_exp_f32_e32 v29, v29
	v_lshlrev_b32_e32 v30, 16, v139
	v_and_b32_e32 v31, 0xffff0000, v139
	v_mov_b32_e32 v33, v27
	v_add_f32_e32 v29, 1.0, v29
	v_rcp_f32_e32 v32, v29
	v_mul_f32_e32 v29, 0x3d372713, v27
	v_mul_f32_e32 v29, v29, v27
	v_fmac_f32_e32 v33, v29, v33
	v_mul_f32_e32 v29, 0x3f4c422a, v33
	v_add_f32_e32 v29, v29, v29
	v_mul_f32_e32 v29, 0xbfb8aa3b, v29
	v_exp_f32_e32 v29, v29
	v_pk_add_f32 v[30:31], v[18:19], v[30:31]
	v_add_f32_e32 v29, 1.0, v29
	v_rcp_f32_e32 v33, v29
	s_nop 0
	v_pk_mul_f32 v[26:27], v[32:33], v[26:27]
	s_nop 0
	v_pk_mul_f32 v[26:27], v[30:31], v[26:27]
	s_nop 0
	v_cvt_pk_bf16_f32 v26, v26, v27
	global_store_dword v[44:45], v26, off
	v_lshl_add_u64 v[44:45], v[44:45], 0, v[50:51]
	s_add_i32 s8, s8, 8
	s_cmp_eq_u32 s8, 0
	s_cbranch_scc0 .LBB0_1367
	v_add_u32_e32 v1, s76, v1
	v_cmp_lt_i32_e32 vcc, s77, v1
	s_or_b64 s[46:47], vcc, s[46:47]
	v_add_u32_e32 v28, s71, v28
	s_andn2_b64 exec, exec, s[46:47]
	s_cbranch_execnz .LBB0_1342

; #define LAS __attribute__((address_space(3)))
; DI f32x4 mfma16(bf16x8 a, bf16x8 b, f32x4 c) { return __builtin_amdgcn_mfma_f32_16x16x32_bf16(a, b, c, 0, 0, 0); }
; template <bool INSYNC> DI void mlstm_phase(const Ctx& C, const bf16* PROJ, const f32x4* TAB, const bf16* PP, bf16* HF, bf16* HB, const XcdBarrier& xbar) {
;     ...
;                 f32x4 accO = (f32x4){0.f, 0.f, 0.f, 0.f}, accN = accO, accP = accO, rsum = accO;
; #pragma unroll
;                 for (int k = 0; k < 8; ++k) { const bf16x8 a = *(const LAS bf16x8*)(Qs + (16 * tr + fr) * LQ + 32 * k + 8 * fq);
;                     accO = mfma16(a, *(const LAS bf16x8*)(ST + (16 * tc + fr) * LQ + 32 * k + 8 * fq), accO);
;                     accN = mfma16(a, *(const LAS bf16x8*)(NB + 32 * k + 8 * fq), accN);
;                     if ((k & 1) == 1) __builtin_amdgcn_sched_barrier(0); }
; #pragma unroll
;                 for (int k = 0; k < 2; ++k) { const bf16x8 p = *(const LAS bf16x8*)(Ps + (16 * tr + fr) * LT + 32 * k + 8 * fq);
;                     accP = tc ? mfma16(p, vf[1][k], accP) : mfma16(p, vf[0][k], accP); rsum = mfma16(p, ones, rsum); }
.LBB0_1467:
	s_waitcnt lgkmcnt(0)
	s_barrier
	ds_read_b128 v[180:183], v128
	ds_read_b128 v[184:187], v130
	ds_read_b128 v[188:191], v131
	ds_read_b128 v[192:195], v128 offset:64
	ds_read_b128 v[196:199], v130 offset:64
	ds_read_b128 v[200:203], v131 offset:64
	ds_read_b128 v[204:207], v128 offset:128
	ds_read_b128 v[230:233], v130 offset:128
	ds_read_b128 v[234:237], v131 offset:128
	ds_read_b128 v[238:241], v128 offset:192
	ds_read_b128 v[242:245], v130 offset:192
	ds_read_b128 v[246:249], v131 offset:192
	ds_read_b128 v[88:91], v128 offset:256
	ds_read_b128 v[100:103], v130 offset:256
	ds_read_b128 v[104:107], v131 offset:256
	s_waitcnt lgkmcnt(12)
	v_mfma_f32_16x16x32_bf16 v[96:99], v[180:183], v[184:187], 0
	v_mfma_f32_16x16x32_bf16 v[92:95], v[180:183], v[188:191], 0
	s_waitcnt lgkmcnt(9)
	v_mfma_f32_16x16x32_bf16 v[96:99], v[192:195], v[196:199], v[96:99]
	v_mfma_f32_16x16x32_bf16 v[92:95], v[192:195], v[200:203], v[92:95]
	ds_read_b128 v[180:183], v128 offset:320
	ds_read_b128 v[184:187], v130 offset:320
	ds_read_b128 v[188:191], v131 offset:320
	ds_read_b128 v[192:195], v128 offset:384
	ds_read_b128 v[196:199], v130 offset:384
	ds_read_b128 v[200:203], v131 offset:384
	s_waitcnt lgkmcnt(12)
	v_mfma_f32_16x16x32_bf16 v[96:99], v[204:207], v[230:233], v[96:99]
	v_mfma_f32_16x16x32_bf16 v[92:95], v[204:207], v[234:237], v[92:95]
	ds_read_b128 v[204:207], v128 offset:448
	ds_read_b128 v[230:233], v130 offset:448
	ds_read_b128 v[234:237], v131 offset:448
	s_waitcnt lgkmcnt(12)
	v_mfma_f32_16x16x32_bf16 v[96:99], v[238:241], v[242:245], v[96:99]
	v_mfma_f32_16x16x32_bf16 v[92:95], v[238:241], v[246:249], v[92:95]
	ds_read_b128 v[84:87], v167
	ds_read_b128 v[72:75], v167 offset:64
	ds_read_b128 v[80:83], v167 offset:2304
	s_waitcnt lgkmcnt(12)
	v_mfma_f32_16x16x32_bf16 v[96:99], v[88:91], v[100:103], v[96:99]
	v_mfma_f32_16x16x32_bf16 v[92:95], v[88:91], v[104:107], v[92:95]
	ds_read_b128 v[76:79], v167 offset:2368
	s_waitcnt lgkmcnt(10)
	v_mfma_f32_16x16x32_bf16 v[96:99], v[180:183], v[184:187], v[96:99]
	v_mfma_f32_16x16x32_bf16 v[92:95], v[180:183], v[188:191], v[92:95]
	s_waitcnt lgkmcnt(7)
	v_mfma_f32_16x16x32_bf16 v[96:99], v[192:195], v[196:199], v[96:99]
	v_mfma_f32_16x16x32_bf16 v[92:95], v[192:195], v[200:203], v[92:95]
	s_waitcnt lgkmcnt(4)
	v_mfma_f32_16x16x32_bf16 v[96:99], v[204:207], v[230:233], v[96:99]
	v_mfma_f32_16x16x32_bf16 v[92:95], v[204:207], v[234:237], v[92:95]
	ds_read_b128 v[100:103], v169
	v_cndmask_b32_e64 v5, 0, 1, s[10:11]
	v_cmp_ne_u32_e64 s[52:53], 1, v5
	s_andn2_b64 vcc, exec, s[10:11]
	s_mov_b64 s[20:21], -1
	s_cbranch_vccnz .LBB0_1469
	s_waitcnt lgkmcnt(0)
	v_mfma_f32_16x16x32_bf16 v[88:91], v[100:103], v[80:83], 0
	s_mov_b64 s[20:21], 0
